# v83 + one static s_setprio 1 for the leading half (waves 0..3) in every GEMM phase
# speedup vs baseline: 1.0072x; 1.0072x over previous
.LBB0_164:
	s_mov_b64 s[6:7], s[0:1]
	s_setprio 0
	s_getreg_b32 s8, hwreg(HW_REG_XCC_ID, 0, 4)
	s_waitcnt vmcnt(0)
	s_barrier
	s_and_saveexec_b64 s[4:5], s[44:45]
	s_cbranch_execz .LBB0_217
	s_add_i32 s9, 0, 0x23fe0
	v_mov_b32_e32 v0, s9
	s_load_dwordx2 s[6:7], s[6:7], 0x80
	s_waitcnt vmcnt(0) expcnt(0) lgkmcnt(0)
	ds_read_b32 v2, v0
	s_add_i32 s9, 0, 0x23fe4
	v_mov_b32_e32 v0, s9
	ds_read_b32 v0, v0
	s_and_b32 s33, s8, 15
	s_waitcnt lgkmcnt(1)
	v_cmp_ne_u32_e32 vcc, 0, v2
	s_cbranch_vccnz .LBB0_180
	s_load_dword s8, s[0:1], 0x90
	s_mov_b32 s56, 1
	v_mov_b32_e32 v16, 0
	s_waitcnt lgkmcnt(0)
	s_mul_i32 s47, s53, s8
	s_add_u32 s8, s6, 0x4200
	s_addc_u32 s9, s7, 0
	s_add_u32 s10, s6, 0x4400
	s_addc_u32 s11, s7, 0
	s_add_u32 s12, s6, 0x4500
	s_addc_u32 s13, s7, 0
	s_add_u32 s14, s6, 0x4600
	s_addc_u32 s15, s7, 0
	s_add_u32 s16, s6, 0x4700
	s_addc_u32 s17, s7, 0
	s_add_u32 s18, s6, 0x4800
	s_addc_u32 s19, s7, 0
	s_add_u32 s20, s6, 0x4900
	s_addc_u32 s21, s7, 0
	s_add_u32 s22, s6, 0x4a00
	s_addc_u32 s23, s7, 0
	s_add_u32 s24, s6, 0x4b00
	s_addc_u32 s25, s7, 0
	s_add_u32 s26, s6, 0x4c00
	s_addc_u32 s27, s7, 0
	s_add_u32 s28, s6, 0x4d00
	s_addc_u32 s29, s7, 0
	s_add_u32 s30, s6, 0x4e00
	s_addc_u32 s31, s7, 0
	s_add_u32 s34, s6, 0x4f00
	s_addc_u32 s35, s7, 0
	s_add_u32 s36, s6, 0x5000
	s_addc_u32 s37, s7, 0
	s_add_u32 s38, s6, 0x5100
	s_addc_u32 s39, s7, 0
	s_add_u32 s40, s6, 0x5200
	s_addc_u32 s41, s7, 0
	s_add_u32 s42, s6, 0x5300
	s_mul_i32 s47, s47, s52
	s_addc_u32 s43, s7, 0
	s_branch .LBB0_168

.LBB0_220:
	s_cmp_eq_u32 s14, 0
	s_cbranch_scc0 .Lprio03_0
	s_setprio 1

.LBB0_233:
	s_mov_b64 s[6:7], s[0:1]
	s_setprio 0
	s_getreg_b32 s8, hwreg(HW_REG_XCC_ID, 0, 4)
	s_waitcnt vmcnt(0)
	s_waitcnt vmcnt(0)
	v_add_u32_e32 v254, v254, v255
	v_cmp_ne_u32_e32 vcc, 17, v254
	s_nop 3
	s_cmp_eq_u64 vcc, 0
	s_cselect_b32 s99, 1, 0
	s_cmpk_lg_i32 s52, 0x100
	s_cselect_b32 s99, 0, s99
	s_barrier
	s_and_saveexec_b64 s[4:5], s[44:45]
	s_xor_b64 s[4:5], exec, s[4:5]
	s_cbranch_execz .LBB0_286
	s_cmp_eq_u32 s99, 0
	s_cbranch_scc1 .Lfb_skip_0
	s_load_dwordx2 s[8:9], s[0:1], 0x80
	s_and_b32 s10, s2, 7
	s_lshl_b32 s10, s10, 8
	s_add_i32 s10, s10, 0x1000
	s_lshr_b32 s11, s2, 3
	s_lshl_b32 s11, s11, 2
	v_mov_b32_e32 v1, s11
	v_mov_b32_e32 v0, 1
	s_mov_b32 s13, 0
	s_mov_b64 s[16:17], exec
	s_waitcnt lgkmcnt(0)
	s_add_u32 s8, s8, s10
	s_addc_u32 s9, s9, 0
	global_store_dword v1, v0, s[8:9]
	buffer_inv sc1
	s_mov_b64 exec, 0xffffffff
	v_mbcnt_lo_u32_b32 v4, -1, 0
	v_lshlrev_b32_e32 v4, 2, v4
	v_mov_b32_e32 v0, 1

.LBB0_400:
	s_mov_b64 s[6:7], s[0:1]
	s_setprio 0
	s_getreg_b32 s8, hwreg(HW_REG_XCC_ID, 0, 4)
	s_waitcnt vmcnt(0)
	s_barrier
	s_and_saveexec_b64 s[4:5], s[44:45]
	s_cbranch_execz .LBB0_452
	s_add_i32 s9, 0, 0x23fe0
	v_mov_b32_e32 v0, s9
	s_load_dwordx2 s[6:7], s[6:7], 0x80
	s_waitcnt vmcnt(0) expcnt(0) lgkmcnt(0)
	ds_read_b32 v2, v0
	s_add_i32 s9, 0, 0x23fe4
	v_mov_b32_e32 v0, s9
	ds_read_b32 v0, v0
	s_and_b32 s33, s8, 15
	s_waitcnt lgkmcnt(1)
	v_cmp_ne_u32_e32 vcc, 0, v2
	s_cbranch_vccnz .LBB0_416
	s_load_dword s8, s[0:1], 0x90
	s_mov_b32 s55, 1
	v_mov_b32_e32 v16, 0
	s_waitcnt lgkmcnt(0)
	s_mul_i32 s54, s53, s8
	s_add_u32 s8, s6, 0x4200
	s_addc_u32 s9, s7, 0
	s_add_u32 s10, s6, 0x4400
	s_addc_u32 s11, s7, 0
	s_add_u32 s12, s6, 0x4500
	s_addc_u32 s13, s7, 0
	s_add_u32 s14, s6, 0x4600
	s_addc_u32 s15, s7, 0
	s_add_u32 s16, s6, 0x4700
	s_addc_u32 s17, s7, 0
	s_add_u32 s18, s6, 0x4800
	s_addc_u32 s19, s7, 0
	s_add_u32 s20, s6, 0x4900
	s_addc_u32 s21, s7, 0
	s_add_u32 s22, s6, 0x4a00
	s_addc_u32 s23, s7, 0
	s_add_u32 s24, s6, 0x4b00
	s_addc_u32 s25, s7, 0
	s_add_u32 s26, s6, 0x4c00
	s_addc_u32 s27, s7, 0
	s_add_u32 s28, s6, 0x4d00
	s_addc_u32 s29, s7, 0
	s_add_u32 s30, s6, 0x4e00
	s_addc_u32 s31, s7, 0
	s_add_u32 s34, s6, 0x4f00
	s_addc_u32 s35, s7, 0
	s_add_u32 s36, s6, 0x5000
	s_addc_u32 s37, s7, 0
	s_add_u32 s38, s6, 0x5100
	s_addc_u32 s39, s7, 0
	s_add_u32 s40, s6, 0x5200
	s_addc_u32 s41, s7, 0
	s_add_u32 s42, s6, 0x5300
	s_mul_i32 s54, s54, s52
	s_addc_u32 s43, s7, 0
	s_branch .LBB0_404

.LBB0_463:
	s_mov_b64 s[6:7], s[0:1]
	s_setprio 0
	s_getreg_b32 s8, hwreg(HW_REG_XCC_ID, 0, 4)
	s_waitcnt vmcnt(0)
	s_barrier
	s_and_saveexec_b64 s[4:5], s[44:45]
	v_readlane_b32 s70, v250, 2
	v_readlane_b32 s71, v250, 3
	s_cbranch_execz .LBB0_515
	s_add_i32 s9, 0, 0x23fe0
	v_mov_b32_e32 v0, s9
	s_load_dwordx2 s[6:7], s[6:7], 0x80
	s_waitcnt vmcnt(0) expcnt(0) lgkmcnt(0)
	ds_read_b32 v2, v0
	s_add_i32 s9, 0, 0x23fe4
	v_mov_b32_e32 v0, s9
	ds_read_b32 v0, v0
	s_and_b32 s33, s8, 15
	s_waitcnt lgkmcnt(1)
	v_cmp_ne_u32_e32 vcc, 0, v2
	s_cbranch_vccnz .LBB0_479
	s_load_dword s8, s[0:1], 0x90
	s_mov_b32 s55, 1
	v_mov_b32_e32 v16, 0
	s_waitcnt lgkmcnt(0)
	s_mul_i32 s54, s53, s8
	s_add_u32 s8, s6, 0x4200
	s_addc_u32 s9, s7, 0
	s_add_u32 s10, s6, 0x4400
	s_addc_u32 s11, s7, 0
	s_add_u32 s12, s6, 0x4500
	s_addc_u32 s13, s7, 0
	s_add_u32 s16, s6, 0x4600
	s_addc_u32 s17, s7, 0
	s_add_u32 s18, s6, 0x4700
	s_addc_u32 s19, s7, 0
	s_add_u32 s20, s6, 0x4800
	s_addc_u32 s21, s7, 0
	s_add_u32 s22, s6, 0x4900
	s_addc_u32 s23, s7, 0
	s_add_u32 s24, s6, 0x4a00
	s_addc_u32 s25, s7, 0
	s_add_u32 s26, s6, 0x4b00
	s_addc_u32 s27, s7, 0
	s_add_u32 s28, s6, 0x4c00
	s_addc_u32 s29, s7, 0
	s_add_u32 s30, s6, 0x4d00
	s_addc_u32 s31, s7, 0
	s_add_u32 s34, s6, 0x4e00
	s_addc_u32 s35, s7, 0
	s_add_u32 s36, s6, 0x4f00
	s_addc_u32 s37, s7, 0
	s_add_u32 s38, s6, 0x5000
	s_addc_u32 s39, s7, 0
	s_add_u32 s40, s6, 0x5100
	s_addc_u32 s41, s7, 0
	s_add_u32 s42, s6, 0x5200
	s_addc_u32 s43, s7, 0
	s_add_u32 s48, s6, 0x5300
	s_mul_i32 s54, s54, s52
	s_addc_u32 s49, s7, 0
	s_branch .LBB0_467

.LBB0_518:
	s_mov_b64 s[6:7], s[0:1]
	s_setprio 0
	s_getreg_b32 s8, hwreg(HW_REG_XCC_ID, 0, 4)
	s_waitcnt vmcnt(0)
	s_barrier
	s_and_saveexec_b64 s[4:5], s[44:45]
	s_cbranch_execz .LBB0_570
	s_cmp_eq_u32 s99, 0
	s_cbranch_scc1 .Lfb_skip_1
	s_load_dwordx2 s[8:9], s[0:1], 0x80
	s_and_b32 s10, s2, 7
	s_lshl_b32 s10, s10, 8
	s_add_i32 s10, s10, 0x1000
	s_lshr_b32 s11, s2, 3
	s_lshl_b32 s11, s11, 2
	v_mov_b32_e32 v1, s11
	v_mov_b32_e32 v0, 2
	s_mov_b32 s13, 0
	s_mov_b64 s[16:17], exec
	s_waitcnt lgkmcnt(0)
	s_add_u32 s8, s8, s10
	s_addc_u32 s9, s9, 0
	global_store_dword v1, v0, s[8:9]
	buffer_inv sc1
	s_mov_b64 exec, 0xffffffff
	v_mbcnt_lo_u32_b32 v4, -1, 0
	v_lshlrev_b32_e32 v4, 2, v4
	v_mov_b32_e32 v0, 2

.LBB0_579:
	s_cmp_eq_u32 s8, 0
	s_cbranch_scc0 .Lprio03_1
	s_setprio 1

.LBB0_612:
	s_mov_b64 s[8:9], s[0:1]
	s_waitcnt lgkmcnt(0)
	s_setprio 0
	s_getreg_b32 s10, hwreg(HW_REG_XCC_ID, 0, 4)
	s_waitcnt vmcnt(0)
	s_barrier
	s_and_saveexec_b64 s[6:7], s[44:45]
	s_cbranch_execz .LBB0_664
	s_cmp_eq_u32 s99, 0
	s_cbranch_scc1 .Lfb_skip_2
	s_load_dwordx2 s[8:9], s[0:1], 0x80
	s_and_b32 s10, s2, 7
	s_lshl_b32 s10, s10, 8
	s_add_i32 s10, s10, 0x1000
	s_lshr_b32 s11, s2, 3
	s_lshl_b32 s11, s11, 2
	v_mov_b32_e32 v1, s11
	v_mov_b32_e32 v0, 3
	s_mov_b32 s13, 0
	s_mov_b64 s[16:17], exec
	s_waitcnt lgkmcnt(0)
	s_add_u32 s8, s8, s10
	s_addc_u32 s9, s9, 0
	global_store_dword v1, v0, s[8:9]
	buffer_inv sc1
	s_mov_b64 exec, 0xffffffff
	v_mbcnt_lo_u32_b32 v4, -1, 0
	v_lshlrev_b32_e32 v4, 2, v4
	v_mov_b32_e32 v0, 3

.LBB0_667:
	s_cmp_eq_u32 s22, 0
	s_cbranch_scc0 .Lprio03_2
	s_setprio 1

.LBB0_1112:
	s_mov_b64 s[8:9], s[0:1]
	s_setprio 0
	s_getreg_b32 s10, hwreg(HW_REG_XCC_ID, 0, 4)
	s_waitcnt vmcnt(0)
	s_barrier
	s_and_saveexec_b64 s[6:7], s[44:45]
	s_cbranch_execz .LBB0_1164
	s_cmp_eq_u32 s99, 0
	s_cbranch_scc1 .Lfb_skip_3
	s_load_dwordx2 s[8:9], s[0:1], 0x80
	s_and_b32 s10, s2, 7
	s_lshl_b32 s10, s10, 8
	s_add_i32 s10, s10, 0x1000
	s_lshr_b32 s11, s2, 3
	s_lshl_b32 s11, s11, 2
	v_mov_b32_e32 v1, s11
	v_mov_b32_e32 v0, 4
	s_mov_b32 s13, 0
	s_mov_b64 s[16:17], exec
	s_waitcnt lgkmcnt(0)
	s_add_u32 s8, s8, s10
	s_addc_u32 s9, s9, 0
	global_store_dword v1, v0, s[8:9]
	buffer_inv sc1
	s_mov_b64 exec, 0xffffffff
	v_mbcnt_lo_u32_b32 v4, -1, 0
	v_lshlrev_b32_e32 v4, 2, v4
	v_mov_b32_e32 v0, 4

.LBB0_1210:
	s_mov_b64 s[8:9], s[0:1]
	s_setprio 0
	s_getreg_b32 s10, hwreg(HW_REG_XCC_ID, 0, 4)
	s_waitcnt vmcnt(0)
	s_waitcnt lgkmcnt(0)
	s_barrier
	s_and_saveexec_b64 s[6:7], s[44:45]
	s_cbranch_execz .LBB0_1262
	s_cmp_eq_u32 s99, 0
	s_cbranch_scc1 .Lfb_skip_4
	s_load_dwordx2 s[8:9], s[0:1], 0x80
	s_and_b32 s10, s2, 7
	s_lshl_b32 s10, s10, 8
	s_add_i32 s10, s10, 0x1000
	s_lshr_b32 s11, s2, 3
	s_lshl_b32 s11, s11, 2
	v_mov_b32_e32 v1, s11
	v_mov_b32_e32 v0, 5
	s_mov_b32 s13, 0
	s_mov_b64 s[16:17], exec
	s_waitcnt lgkmcnt(0)
	s_add_u32 s8, s8, s10
	s_addc_u32 s9, s9, 0
	global_store_dword v1, v0, s[8:9]
	buffer_inv sc1
	s_mov_b64 exec, 0xffffffff
	v_mbcnt_lo_u32_b32 v4, -1, 0
	v_lshlrev_b32_e32 v4, 2, v4
	v_mov_b32_e32 v0, 5

.LBB0_1278:
	s_mov_b64 s[8:9], s[0:1]
	s_setprio 0
	s_getreg_b32 s10, hwreg(HW_REG_XCC_ID, 0, 4)
	s_waitcnt vmcnt(0)
	s_barrier
	s_and_saveexec_b64 s[6:7], s[44:45]
	s_cbranch_execz .LBB0_1330
	s_add_i32 s11, 0, 0x23fe0
	v_mov_b32_e32 v0, s11
	s_load_dwordx2 s[8:9], s[8:9], 0x80
	s_waitcnt vmcnt(0) expcnt(0) lgkmcnt(0)
	ds_read_b32 v2, v0
	s_add_i32 s11, 0, 0x23fe4
	v_mov_b32_e32 v0, s11
	ds_read_b32 v0, v0
	s_and_b32 s33, s10, 15
	s_waitcnt lgkmcnt(1)
	v_cmp_ne_u32_e32 vcc, 0, v2
	s_cbranch_vccnz .LBB0_1294
	s_load_dword s10, s[0:1], 0x90
	s_mov_b32 s55, 1
	v_mov_b32_e32 v16, 0
	s_waitcnt lgkmcnt(0)
	s_mul_i32 s54, s53, s10
	s_add_u32 s10, s8, 0x4200
	s_addc_u32 s11, s9, 0
	s_add_u32 s12, s8, 0x4400
	s_addc_u32 s13, s9, 0
	s_add_u32 s16, s8, 0x4500
	s_addc_u32 s17, s9, 0
	s_add_u32 s18, s8, 0x4600
	s_addc_u32 s19, s9, 0
	s_add_u32 s20, s8, 0x4700
	s_addc_u32 s21, s9, 0
	s_add_u32 s22, s8, 0x4800
	s_addc_u32 s23, s9, 0
	s_add_u32 s24, s8, 0x4900
	s_addc_u32 s25, s9, 0
	s_add_u32 s26, s8, 0x4a00
	s_addc_u32 s27, s9, 0
	s_add_u32 s28, s8, 0x4b00
	s_addc_u32 s29, s9, 0
	s_add_u32 s30, s8, 0x4c00
	s_addc_u32 s31, s9, 0
	s_add_u32 s34, s8, 0x4d00
	s_addc_u32 s35, s9, 0
	s_add_u32 s36, s8, 0x4e00
	s_addc_u32 s37, s9, 0
	s_add_u32 s38, s8, 0x4f00
	s_addc_u32 s39, s9, 0
	s_add_u32 s40, s8, 0x5000
	s_addc_u32 s41, s9, 0
	s_add_u32 s42, s8, 0x5100
	s_addc_u32 s43, s9, 0
	s_add_u32 s48, s8, 0x5200
	s_addc_u32 s49, s9, 0
	s_add_u32 s50, s8, 0x5300
	s_mul_i32 s54, s54, s52
	s_addc_u32 s51, s9, 0
	s_branch .LBB0_1282

.LBB0_1349:
	s_mov_b64 s[8:9], s[0:1]
	s_setprio 0
	s_getreg_b32 s10, hwreg(HW_REG_XCC_ID, 0, 4)
	s_waitcnt vmcnt(0)
	s_barrier
	s_and_saveexec_b64 s[6:7], s[44:45]
	s_cbranch_execz .LBB0_1401
	s_cmp_eq_u32 s99, 0
	s_cbranch_scc1 .Lfb_skip_5
	s_load_dwordx2 s[8:9], s[0:1], 0x80
	s_and_b32 s10, s2, 7
	s_lshl_b32 s10, s10, 8
	s_add_i32 s10, s10, 0x1000
	s_lshr_b32 s11, s2, 3
	s_lshl_b32 s11, s11, 2
	v_mov_b32_e32 v1, s11
	v_mov_b32_e32 v0, 6
	s_mov_b32 s13, 0
	s_mov_b64 s[16:17], exec
	s_waitcnt lgkmcnt(0)
	s_add_u32 s8, s8, s10
	s_addc_u32 s9, s9, 0
	global_store_dword v1, v0, s[8:9]
	buffer_inv sc1
	s_mov_b64 exec, 0xffffffff
	v_mbcnt_lo_u32_b32 v4, -1, 0
	v_lshlrev_b32_e32 v4, 2, v4
	v_mov_b32_e32 v0, 6

.LBB0_1443:
	s_mov_b64 s[8:9], s[0:1]
	s_setprio 0
	s_getreg_b32 s10, hwreg(HW_REG_XCC_ID, 0, 4)
	s_waitcnt vmcnt(0)
	s_waitcnt lgkmcnt(0)
	s_barrier
	s_and_saveexec_b64 s[6:7], s[44:45]
	s_cbranch_execz .LBB0_1495
	s_cmp_eq_u32 s99, 0
	s_cbranch_scc1 .Lfb_skip_6
	s_load_dwordx2 s[8:9], s[0:1], 0x80
	s_and_b32 s10, s2, 7
	s_lshl_b32 s10, s10, 8
	s_add_i32 s10, s10, 0x1000
	s_lshr_b32 s11, s2, 3
	s_lshl_b32 s11, s11, 2
	v_mov_b32_e32 v1, s11
	v_mov_b32_e32 v0, 7
	s_mov_b32 s13, 0
	s_mov_b64 s[16:17], exec
	s_waitcnt lgkmcnt(0)
	s_add_u32 s8, s8, s10
	s_addc_u32 s9, s9, 0
	global_store_dword v1, v0, s[8:9]
	buffer_inv sc1
	s_mov_b64 exec, 0xffffffff
	v_mbcnt_lo_u32_b32 v4, -1, 0
	v_lshlrev_b32_e32 v4, 2, v4
	v_mov_b32_e32 v0, 7

.LBB0_1498:
	s_cmp_eq_u32 s20, 0
	s_cbranch_scc0 .Lprio03_6
	s_setprio 1

.LBB0_1935:
	s_mov_b64 s[8:9], s[0:1]
	s_setprio 0
	s_getreg_b32 s10, hwreg(HW_REG_XCC_ID, 0, 4)
	s_waitcnt vmcnt(0)
	s_barrier
	s_and_saveexec_b64 s[6:7], s[44:45]
	s_cbranch_execz .LBB0_1987
	s_add_i32 s11, 0, 0x23fe0
	s_waitcnt vmcnt(17)
	v_mov_b32_e32 v0, s11
	s_load_dwordx2 s[8:9], s[8:9], 0x80
	s_waitcnt vmcnt(0) expcnt(0) lgkmcnt(0)
	ds_read_b32 v2, v0
	s_add_i32 s11, 0, 0x23fe4
	v_mov_b32_e32 v0, s11
	ds_read_b32 v0, v0
	s_and_b32 s33, s10, 15
	s_waitcnt lgkmcnt(1)
	v_cmp_ne_u32_e32 vcc, 0, v2
	s_cbranch_vccnz .LBB0_1951
	s_load_dword s10, s[0:1], 0x90
	s_mov_b32 s55, 1
	v_mov_b32_e32 v16, 0
	s_waitcnt lgkmcnt(0)
	s_mul_i32 s54, s53, s10
	s_add_u32 s10, s8, 0x4200
	s_addc_u32 s11, s9, 0
	s_add_u32 s12, s8, 0x4400
	s_addc_u32 s13, s9, 0
	s_add_u32 s14, s8, 0x4500
	s_addc_u32 s15, s9, 0
	s_add_u32 s16, s8, 0x4600
	s_addc_u32 s17, s9, 0
	s_add_u32 s18, s8, 0x4700
	s_addc_u32 s19, s9, 0
	s_add_u32 s20, s8, 0x4800
	s_addc_u32 s21, s9, 0
	s_add_u32 s22, s8, 0x4900
	s_addc_u32 s23, s9, 0
	s_add_u32 s24, s8, 0x4a00
	s_addc_u32 s25, s9, 0
	s_add_u32 s26, s8, 0x4b00
	s_addc_u32 s27, s9, 0
	s_add_u32 s28, s8, 0x4c00
	s_addc_u32 s29, s9, 0
	s_add_u32 s30, s8, 0x4d00
	s_addc_u32 s31, s9, 0
	s_add_u32 s34, s8, 0x4e00
	s_addc_u32 s35, s9, 0
	s_add_u32 s36, s8, 0x4f00
	s_addc_u32 s37, s9, 0
	s_add_u32 s38, s8, 0x5000
	s_addc_u32 s39, s9, 0
	s_add_u32 s40, s8, 0x5100
	s_addc_u32 s41, s9, 0
	s_add_u32 s42, s8, 0x5200
	s_addc_u32 s43, s9, 0
	s_add_u32 s48, s8, 0x5300
	s_mul_i32 s54, s54, s52
	s_addc_u32 s49, s9, 0
	s_branch .LBB0_1939

.LBB0_2034:
	s_mov_b64 s[8:9], s[0:1]
	s_setprio 0
	s_getreg_b32 s10, hwreg(HW_REG_XCC_ID, 0, 4)
	s_waitcnt vmcnt(0)
	s_waitcnt lgkmcnt(0)
	s_barrier
	s_and_saveexec_b64 s[6:7], s[44:45]
	s_cbranch_execz .LBB0_2086
	s_add_i32 s11, 0, 0x23fe0
	v_mov_b32_e32 v0, s11
	s_load_dwordx2 s[8:9], s[8:9], 0x80
	s_waitcnt vmcnt(0) expcnt(0) lgkmcnt(0)
	ds_read_b32 v2, v0
	s_add_i32 s11, 0, 0x23fe4
	v_mov_b32_e32 v0, s11
	ds_read_b32 v0, v0
	s_and_b32 s33, s10, 15
	s_waitcnt lgkmcnt(1)
	v_cmp_ne_u32_e32 vcc, 0, v2
	s_cbranch_vccnz .LBB0_2050
	s_load_dword s10, s[0:1], 0x90
	s_mov_b32 s54, 1
	v_mov_b32_e32 v16, 0
	s_waitcnt lgkmcnt(0)
	s_mul_i32 s47, s53, s10
	s_add_u32 s10, s8, 0x4200
	s_addc_u32 s11, s9, 0
	s_add_u32 s12, s8, 0x4400
	s_addc_u32 s13, s9, 0
	s_add_u32 s14, s8, 0x4500
	s_addc_u32 s15, s9, 0
	s_add_u32 s16, s8, 0x4600
	s_addc_u32 s17, s9, 0
	s_add_u32 s18, s8, 0x4700
	s_addc_u32 s19, s9, 0
	s_add_u32 s20, s8, 0x4800
	s_addc_u32 s21, s9, 0
	s_add_u32 s22, s8, 0x4900
	s_addc_u32 s23, s9, 0
	s_add_u32 s24, s8, 0x4a00
	s_addc_u32 s25, s9, 0
	s_add_u32 s26, s8, 0x4b00
	s_addc_u32 s27, s9, 0
	s_add_u32 s28, s8, 0x4c00
	s_addc_u32 s29, s9, 0
	s_add_u32 s30, s8, 0x4d00
	s_addc_u32 s31, s9, 0
	s_add_u32 s34, s8, 0x4e00
	s_addc_u32 s35, s9, 0
	s_add_u32 s36, s8, 0x4f00
	s_addc_u32 s37, s9, 0
	s_add_u32 s38, s8, 0x5000
	s_addc_u32 s39, s9, 0
	s_add_u32 s40, s8, 0x5100
	s_addc_u32 s41, s9, 0
	s_add_u32 s42, s8, 0x5200
	s_addc_u32 s43, s9, 0
	s_add_u32 s44, s8, 0x5300
	s_mul_i32 s47, s47, s52
	s_addc_u32 s45, s9, 0
	s_branch .LBB0_2038

.LBB0_2099:
	s_cmp_eq_u32 s16, 0
	s_cbranch_scc0 .Lprio03_8
	s_setprio 1
